# KSPLIT 1280->1152: rebalance after the faster scan (less output-projection K in the mixers shadow)
# speedup vs baseline: 1.0072x; 1.0014x over previous
;     __host__ __device__ bool next(int i, Unit& u) const {
;         const long L = (long)i * G + c; if (L >= nwg) return false;
;         int wgid = (int)L; { const int q = nwg / NXCD, r = nwg % NXCD, xcd = wgid % NXCD, off = wgid / NXCD; wgid = (xcd < r ? xcd * (q + 1) : r * (q + 1) + (xcd - r) * q) + off; }
;         const int nig = WGM * nN, gid = wgid / nig, fm = gid * WGM, gsz = (nM - fm) < WGM ? (nM - fm) : WGM;
;         u.pm = fm + ((wgid % nig) % gsz); u.pn = (wgid % nig) / gsz; return true;
; __global__ void __launch_bounds__(NWAVES * 64, 2) hybrid_fwd(Args A) {
;     ...
;             if (s == 0 && EN(1)) { pg8::Gemm g{WS_PTR(const bf16, WS_HB), WS_PTR(const bf16, WS_WINT) + (size_t)l * DINP * D, M, DINP, D, D}; pg8::StaticOrder S; S.init(M, DINP, C.G, C.bid);
;                 pg8::EpiU E{WS_PTR(bf16, WS_U), WS_PTR(const float, WS_SS) + (size_t)l * M};
;                 pg8::gemm_phase<pg8::EpiU, pg8::StaticOrder, G1_ALIGN, G1_SP2>(C.lds, g, S, E); }
;             else if (s == 1 && EN(2)) phase_prep(A, C, l);
;             else if ((s == 2 && EN(3)) || (s == 3 && EN(4)) || (s == 4 && EN(5))) {
;                 const bool split = C.G >= 192; bool go = (s == 4); int k0 = split ? KSPLIT : 0, kl = D - k0, gg = C.G, cc = C.bid, mrows = M; size_t roff = 0;
;                 if (s == 2) { go = phase_mixers(A, C, l, rep ? DUP_UN : 7); k0 = 0; kl = KSPLIT; gg = C.G - 128; cc = C.bid - 128; mrows = MP; }
;                 if (s == 3) { phase_post(A, C, l, split ? 8 : 0); go = split && C.bid < 8 && !rep; k0 = 0; kl = KSPLIT; gg = 8; cc = C.bid; mrows = MS; roff = (size_t)MP * D; }
;                 if (go) { pg8::Gemm g{WS_PTR(const bf16, WS_XN) + roff + k0, WS_PTR(const bf16, WS_WOUTT) + (size_t)l * D * D + k0, mrows, D, kl, D}; pg8::StaticOrder S; S.init(mrows, D, gg, cc);
;                     const bool first = (l == 0) && (s != 4 || !split);
;                     float* Hout = ((rep && s == 4) ? WS_PTR(float, WS_U) : A.out) + roff;
;                     pg8::EpiResN E{Hout, first ? (s == 3 ? A.in[I_XS] : A.in[I_XP]) : Hout, first ? A.in[I_XS] - (size_t)MP * D : Hout, WS_PTR(bf16, WS_HB), WS_PTR(float, WS_SS) + (size_t)(l + 1) * M, s == 4 && !rep};
.LBB0_14:
	v_readlane_b32 s12, v253, 0
	s_cmpk_lt_i32 s12, 0xb16
	s_cselect_b64 s[2:3], -1, 0
	v_writelane_b32 v253, s2, 11
	s_load_dword s13, s[0:1], 0xe8
	s_load_dwordx4 s[16:19], s[0:1], 0xc0
	s_load_dwordx2 s[14:15], s[0:1], 0xd0
	v_writelane_b32 v253, s3, 12
	s_ashr_i32 s2, s12, 31
	v_writelane_b32 v253, s2, 13
	s_lshr_b32 s2, s2, 29
	s_add_i32 s2, s12, s2
	s_ashr_i32 s9, s2, 3
	s_and_b32 s2, s2, -8
	s_sub_i32 s10, s12, s2
	s_mul_i32 s2, s10, 0x162
	s_add_i32 s11, s2, 6
	s_waitcnt lgkmcnt(0)
	s_ashr_i32 s2, s13, 31
	s_cmpk_lt_i32 s13, 0xc0
	v_writelane_b32 v253, s2, 14
	s_cselect_b64 s[2:3], -1, 0
	v_writelane_b32 v253, s2, 15
	s_cmpk_gt_i32 s13, 0xbf
	s_load_dwordx16 s[80:95], s[0:1], 0x0
	v_writelane_b32 v253, s3, 16
	s_cselect_b64 s[2:3], -1, 0
	s_and_b64 s[6:7], s[2:3], exec
	s_cselect_b32 s7, 8, 0
	s_cselect_b32 s6, 0x480, 0
	v_writelane_b32 v253, s7, 17
	v_writelane_b32 v253, s6, 18
	s_sub_i32 s6, 0x800, s6
	v_writelane_b32 v253, s6, 19
	s_add_u32 s6, s18, 0x10692000
	v_writelane_b32 v253, s6, 20
	s_addc_u32 s6, s19, 0
	v_writelane_b32 v253, s6, 21
	s_add_u32 s6, s18, 0x10200000
	v_writelane_b32 v253, s6, 22
	s_addc_u32 s6, s19, 0
	v_writelane_b32 v253, s6, 23
	s_add_u32 s6, s18, 0x10bb6000
	v_writelane_b32 v253, s6, 24
	s_addc_u32 s6, s19, 0
	v_writelane_b32 v253, s6, 25
	s_add_u32 s6, s18, 0x10492000
	v_writelane_b32 v253, s6, 26
	s_addc_u32 s6, s19, 0
	s_waitcnt lgkmcnt(0)
	s_cmp_eq_u64 s[92:93], 0
	v_writelane_b32 v253, s6, 27
	s_cselect_b64 s[6:7], -1, 0
	v_writelane_b32 v253, s6, 28
	s_cmp_lg_u64 s[92:93], 0
	s_load_dwordx16 s[36:51], s[0:1], 0x40
	v_writelane_b32 v253, s7, 29
	s_cselect_b64 s[6:7], -1, 0
	v_writelane_b32 v253, s6, 30
	v_mov_b32_e32 v207, 0x260
	v_mov_b32_e32 v229, 0x3727c5ac
	v_writelane_b32 v253, s7, 31
	s_add_u32 s6, s14, 0x8000
	v_writelane_b32 v253, s6, 32
	s_addc_u32 s6, s15, 0
	v_writelane_b32 v253, s6, 33
	s_add_i32 s6, s13, 0xffffff80
	v_writelane_b32 v253, s6, 34
	s_add_i32 s6, s12, 0xffffff80
	s_cmp_lt_i32 s12, 8
	v_writelane_b32 v253, s6, 35
	s_cselect_b64 s[6:7], -1, 0
	s_and_b64 s[2:3], s[6:7], s[2:3]
	v_writelane_b32 v253, s2, 36
	v_mov_b32_e32 v252, 1
	v_mov_b32_e32 v251, 0x7f800000
	v_writelane_b32 v253, s3, 37
	s_add_u32 s2, s82, 0xf0000000
	v_writelane_b32 v253, s2, 38
	s_addc_u32 s2, s83, -1
	s_cmp_lg_u64 s[94:95], 0
	v_writelane_b32 v253, s2, 39
	s_cselect_b64 s[2:3], -1, 0
	v_writelane_b32 v253, s2, 40
	s_cmp_lg_u32 s26, 2
	v_mov_b32_e32 v142, 0x41b17218
	v_writelane_b32 v253, s3, 41
	s_cselect_b64 s[2:3], -1, 0
	v_writelane_b32 v253, s2, 42
	v_mov_b32_e32 v143, 0x3000
	s_movk_i32 s33, 0x7fff
	v_writelane_b32 v253, s3, 43
	s_add_u32 s2, s14, 0x4200
	s_addc_u32 s3, s15, 0
	v_writelane_b32 v253, s2, 44
	s_mov_b32 s96, 0xffff0000
	s_mov_b32 s97, 0x3fb8aa3b
	v_writelane_b32 v253, s3, 45
	s_add_u32 s2, s14, 0x4400
	s_addc_u32 s3, s15, 0
	v_writelane_b32 v253, s2, 46
	s_mov_b32 s20, 0xbfb8aa3b
	s_mov_b32 s21, 0xb2a5705f
	v_writelane_b32 v253, s3, 47
	s_add_u32 s2, s14, 0x4500
	s_addc_u32 s3, s15, 0
	v_writelane_b32 v253, s2, 48
	s_mov_b32 s28, 0x42ce8ed0
	s_mov_b32 s29, 0xc2b17218
	v_writelane_b32 v253, s3, 49
	s_add_u32 s2, s14, 0x4600
	s_addc_u32 s3, s15, 0
	v_writelane_b32 v253, s2, 50
	s_mov_b32 s34, 0x7f800000
	s_mov_b32 s35, 0x800000
	v_writelane_b32 v253, s3, 51
	s_add_u32 s2, s14, 0x4700
	s_addc_u32 s3, s15, 0
	v_writelane_b32 v253, s2, 52
	s_mov_b64 s[22:23], 0x80
	s_nop 0
	v_writelane_b32 v253, s3, 53
	s_add_u32 s2, s14, 0x4800
	s_addc_u32 s3, s15, 0
	v_writelane_b32 v253, s2, 54
	s_nop 1
	v_writelane_b32 v253, s3, 55
	s_add_u32 s2, s14, 0x4900
	s_addc_u32 s3, s15, 0
	v_writelane_b32 v253, s2, 56
	s_nop 1
	v_writelane_b32 v253, s3, 57
	s_add_u32 s2, s14, 0x4a00
	s_addc_u32 s3, s15, 0
	v_writelane_b32 v253, s2, 58
	s_nop 1
	v_writelane_b32 v253, s3, 59
	s_add_u32 s2, s14, 0x4b00
	s_addc_u32 s3, s15, 0
	v_writelane_b32 v253, s2, 60
	s_nop 1
	v_writelane_b32 v253, s3, 61
	s_add_u32 s2, s14, 0x4c00
	s_addc_u32 s3, s15, 0
	v_writelane_b32 v253, s2, 62
	s_nop 1
	v_writelane_b32 v253, s3, 63
	s_add_u32 s2, s14, 0x4d00
	s_addc_u32 s3, s15, 0
	v_writelane_b32 v254, s2, 0
	s_nop 1
	v_writelane_b32 v254, s3, 1
	s_add_u32 s2, s14, 0x4e00
	s_addc_u32 s3, s15, 0
	v_writelane_b32 v254, s2, 2
	s_nop 1
	v_writelane_b32 v254, s3, 3
	s_add_u32 s2, s14, 0x4f00
	s_addc_u32 s3, s15, 0
	v_writelane_b32 v254, s2, 4
	s_nop 1
	v_writelane_b32 v254, s3, 5
	s_add_u32 s2, s14, 0x5000
	s_addc_u32 s3, s15, 0
	v_writelane_b32 v254, s2, 6
	s_nop 1
	v_writelane_b32 v254, s3, 7
	s_add_u32 s2, s14, 0x5100
	s_addc_u32 s3, s15, 0
	v_writelane_b32 v254, s2, 8
	s_nop 1
	v_writelane_b32 v254, s3, 9
	s_add_u32 s2, s14, 0x5200
	s_addc_u32 s3, s15, 0
	v_writelane_b32 v254, s2, 10
	s_nop 1
	v_writelane_b32 v254, s3, 11
	s_add_u32 s2, s14, 0x5300
	s_addc_u32 s3, s15, 0
	v_writelane_b32 v254, s2, 12
	s_cmp_eq_u32 s8, 15
	s_nop 0
	v_writelane_b32 v254, s3, 13
	s_cselect_b64 s[2:3], -1, 0
	v_writelane_b32 v254, s2, 14
	s_cmp_eq_u32 s8, 14
	s_nop 0
	v_writelane_b32 v254, s3, 15
	s_cselect_b64 s[2:3], -1, 0
	v_writelane_b32 v254, s2, 16
	s_cmp_eq_u32 s8, 13
	s_nop 0
	v_writelane_b32 v254, s3, 17
	s_cselect_b64 s[2:3], -1, 0
	v_writelane_b32 v254, s2, 18
; __device__ __forceinline__ unsigned xb_ld(unsigned* p)              { return __hip_atomic_load(p, __ATOMIC_RELAXED, __HIP_MEMORY_SCOPE_AGENT); }
;     __host__ __device__ bool next(int i, Unit& u) const {
;         const long L = (long)i * G + c; if (L >= nwg) return false;
;         int wgid = (int)L; { const int q = nwg / NXCD, r = nwg % NXCD, xcd = wgid % NXCD, off = wgid / NXCD; wgid = (xcd < r ? xcd * (q + 1) : r * (q + 1) + (xcd - r) * q) + off; }
;         const int nig = WGM * nN, gid = wgid / nig, fm = gid * WGM, gsz = (nM - fm) < WGM ? (nM - fm) : WGM;
;         u.pm = fm + ((wgid % nig) % gsz); u.pn = (wgid % nig) / gsz; return true;
; __device__ __forceinline__ void xcd_barrier_complete(unsigned* bar, unsigned x, unsigned& nloc, unsigned& nx) {
;     const unsigned G = gridDim.x * gridDim.y * gridDim.z;
;     unsigned sum, cnt, mine, sp = 0u;
;     for (;;) {
;         sum = 0u; cnt = 0u; mine = 0u;
; #pragma unroll
;         for (unsigned j = 0; j < 16; ++j) { const unsigned c = xb_ld(&bar[XB_XCNT(j)]); sum += c; cnt += (c > 0u) ? 1u : 0u; mine = (j == x) ? c : mine; }
;         if (sum == G) break;
;         __builtin_amdgcn_s_sleep(1);
;         if ((++sp & 255u) == 0u) { if (xb_ld(&bar[XB_TMO])) break; if (sp > XB_SPIN_CAP) { atomicAdd(&bar[XB_TMO], 1u); break; } }
;     }
;     nloc = mine > 0u ? mine : 1u; nx = cnt > 0u ? cnt : 1u;
	s_cmp_eq_u32 s8, 12
	s_nop 0
	v_writelane_b32 v254, s3, 19
	s_cselect_b64 s[2:3], -1, 0
	v_writelane_b32 v254, s2, 20
	s_cmp_eq_u32 s8, 11
	s_nop 0
	v_writelane_b32 v254, s3, 21
	s_cselect_b64 s[2:3], -1, 0
	v_writelane_b32 v254, s2, 22
	s_cmp_eq_u32 s8, 10
	s_nop 0
	v_writelane_b32 v254, s3, 23
	s_cselect_b64 s[2:3], -1, 0
	v_writelane_b32 v254, s2, 24
	s_cmp_eq_u32 s8, 9
	s_nop 0
	v_writelane_b32 v254, s3, 25
	s_cselect_b64 s[2:3], -1, 0
	v_writelane_b32 v254, s2, 26
	s_cmp_eq_u32 s8, 8
	s_nop 0
	v_writelane_b32 v254, s3, 27
	s_cselect_b64 s[2:3], -1, 0
	v_writelane_b32 v254, s2, 28
	s_cmp_eq_u32 s8, 7
	s_nop 0
	v_writelane_b32 v254, s3, 29
	s_cselect_b64 s[2:3], -1, 0
	v_writelane_b32 v254, s2, 30
	s_cmp_eq_u32 s8, 6
	s_nop 0
	v_writelane_b32 v254, s3, 31
	s_cselect_b64 s[2:3], -1, 0
	v_writelane_b32 v254, s2, 32
	s_cmp_eq_u32 s8, 5
	s_nop 0
	v_writelane_b32 v254, s3, 33
	s_cselect_b64 s[2:3], -1, 0
	v_writelane_b32 v254, s2, 34
	s_cmp_eq_u32 s8, 4
	s_nop 0
	v_writelane_b32 v254, s3, 35
	s_cselect_b64 s[2:3], -1, 0
	v_writelane_b32 v254, s2, 36
	s_cmp_eq_u32 s8, 3
	s_nop 0
	v_writelane_b32 v254, s3, 37
	s_cselect_b64 s[2:3], -1, 0
	v_writelane_b32 v254, s2, 38
	s_cmp_eq_u32 s8, 2
	s_nop 0
	v_writelane_b32 v254, s3, 39
	s_cselect_b64 s[2:3], -1, 0
	v_writelane_b32 v254, s2, 40
	s_cmp_eq_u32 s8, 1
	s_nop 0
	v_writelane_b32 v254, s3, 41
	s_cselect_b64 s[2:3], -1, 0
	v_writelane_b32 v254, s2, 42
	s_cmp_eq_u32 s8, 0
	s_nop 0
	v_writelane_b32 v254, s3, 43
	s_cselect_b64 s[2:3], -1, 0
	v_writelane_b32 v254, s2, 44
	s_nop 1
	v_writelane_b32 v254, s3, 45
	s_lshl_b32 s2, s8, 8
	s_add_u32 s2, s4, s2
	s_addc_u32 s3, s5, 0
	s_add_u32 s4, s2, 0x1400
	s_addc_u32 s5, s3, 0
	v_writelane_b32 v254, s4, 46
	s_add_u32 s2, s2, 0x2400
	s_addc_u32 s3, s3, 0
	v_writelane_b32 v254, s5, 47
	v_writelane_b32 v254, s2, 48
	s_nop 1
	v_writelane_b32 v254, s3, 49
	s_add_u32 s2, s14, 0x7400
	s_addc_u32 s3, s15, 0
	v_writelane_b32 v254, s2, 50
	s_nop 1
	v_writelane_b32 v254, s3, 51
	s_add_u32 s2, s14, 0x7500
	s_addc_u32 s3, s15, 0
	v_writelane_b32 v254, s2, 52
	s_cmp_lt_i32 s10, 6
	s_mulk_i32 s10, 0x163
	v_writelane_b32 v254, s3, 53
	s_cselect_b32 s2, s10, s11
	s_add_i32 s2, s2, s9
	s_mul_hi_i32 s3, s2, 0x2e8ba2e9
	s_lshr_b32 s4, s3, 31
	s_ashr_i32 s3, s3, 5
	s_add_i32 s3, s3, s4
	s_mul_i32 s4, s3, 0xb0
	s_lshl_b32 s5, s3, 3
	s_sub_i32 s4, s2, s4
	s_sub_i32 s2, 0x81, s5
	s_min_u32 s6, s2, 8
	v_cvt_f32_ubyte0_e32 v2, s6
	v_cvt_f32_i32_e32 v1, s4
	v_rcp_iflag_f32_e32 v3, v2
	s_ashr_i32 s2, s4, 30
	s_or_b32 s7, s2, 1
	v_mul_f32_e32 v3, v1, v3
	v_trunc_f32_e32 v3, v3
	v_fma_f32 v1, -v3, v2, v1
	v_cmp_ge_f32_e64 s[2:3], |v1|, v2
	v_lshrrev_b32_e32 v1, 20, v0
	v_lshrrev_b32_e32 v0, 10, v0
	v_or_b32_e32 v0, v0, v1
	v_cvt_i32_f32_e32 v1, v3
	s_and_b64 s[2:3], s[2:3], exec
	s_movk_i32 s2, 0x3ff
	v_and_or_b32 v0, v0, s2, v185
	s_cselect_b32 s2, s7, 0
	v_readfirstlane_b32 s3, v1
	s_add_i32 s2, s3, s2
	s_mul_i32 s3, s2, s6
	s_sub_i32 s3, s4, s3
	s_sext_i32_i16 s3, s3
	s_add_i32 s3, s5, s3
	v_writelane_b32 v254, s3, 54
	s_sext_i32_i16 s2, s2
	v_writelane_b32 v254, s2, 55
	s_add_u32 s2, s14, 0xfc54300
	s_addc_u32 s3, s15, 0
	v_writelane_b32 v254, s2, 56
	v_mov_b32_e32 v1, 0
	v_mov_b32_e32 v98, v1
	v_writelane_b32 v254, s3, 57
	s_add_u32 s2, s14, 0xfc3c000
	v_writelane_b32 v254, s2, 58
	s_addc_u32 s2, s15, 0
	v_writelane_b32 v254, s2, 59
	s_add_i32 s2, 0, 0xd000
	v_writelane_b32 v254, s2, 60
	s_add_i32 s2, 0, 0x3cf0
	v_writelane_b32 v254, s2, 61
	s_mov_b32 s3, 0
	v_writelane_b32 v254, s2, 62
	v_mov_b32_e32 v99, v1
	v_mov_b32_e32 v100, v1
	v_writelane_b32 v254, s3, 63
	v_cmp_eq_u32_e64 s[2:3], 0, v185
	v_mov_b32_e32 v101, v1
	s_mov_b32 s4, 0x3f317217
	v_writelane_b32 v255, s2, 0
	s_mov_b32 s5, 0xc2ce8ed0
	s_mov_b32 s6, 0x42b17218
	v_writelane_b32 v255, s3, 1
	v_cmp_eq_u32_e64 s[2:3], 0, v0
	s_mov_b32 s7, 0xf800000
	s_nop 0
	v_writelane_b32 v255, s2, 2
	s_nop 1
	v_writelane_b32 v255, s3, 3
	s_waitcnt lgkmcnt(0)
	v_writelane_b32 v255, s36, 4
	s_nop 1
	v_writelane_b32 v255, s37, 5
	v_writelane_b32 v255, s38, 6
	v_writelane_b32 v255, s39, 7
	v_writelane_b32 v255, s40, 8
	v_writelane_b32 v255, s41, 9
	v_writelane_b32 v255, s42, 10
	v_writelane_b32 v255, s43, 11
	v_writelane_b32 v255, s44, 12
	v_writelane_b32 v255, s45, 13
	v_writelane_b32 v255, s46, 14
	v_writelane_b32 v255, s47, 15
	v_writelane_b32 v255, s48, 16
	v_writelane_b32 v255, s49, 17
	v_writelane_b32 v255, s50, 18
	v_writelane_b32 v255, s51, 19
	s_load_dwordx16 s[36:51], s[0:1], 0x80
	s_waitcnt lgkmcnt(0)
	v_writelane_b32 v255, s36, 20
	s_nop 1
	v_writelane_b32 v255, s37, 21
	v_writelane_b32 v255, s38, 22
	v_writelane_b32 v255, s39, 23
	v_writelane_b32 v255, s40, 24
	v_writelane_b32 v255, s41, 25
	v_writelane_b32 v255, s42, 26
	v_writelane_b32 v255, s43, 27
	v_writelane_b32 v255, s44, 28
	v_writelane_b32 v255, s45, 29
	v_writelane_b32 v255, s46, 30
	v_writelane_b32 v255, s47, 31
	v_writelane_b32 v255, s48, 32
	v_writelane_b32 v255, s49, 33
	v_writelane_b32 v255, s50, 34
	v_writelane_b32 v255, s51, 35
	s_mov_b32 s98, 0
	v_writelane_b32 v255, s98, 61
	v_writelane_b32 v255, s98, 62
	v_writelane_b32 v255, s98, 63
	s_branch .LBB0_19

; __global__ void __launch_bounds__(NWAVES * 64, 2) hybrid_fwd(Args A) {
;     ...
;                 if (s == 2) { go = phase_mixers(A, C, l, rep ? DUP_UN : 7); k0 = 0; kl = KSPLIT; gg = C.G - 128; cc = C.bid - 128; mrows = MP; }
;                 if (s == 3) { phase_post(A, C, l, split ? 8 : 0); go = split && C.bid < 8 && !rep; k0 = 0; kl = KSPLIT; gg = 8; cc = C.bid; mrows = MS; roff = (size_t)MP * D; }
;                 if (go) { pg8::Gemm g{WS_PTR(const bf16, WS_XN) + roff + k0, WS_PTR(const bf16, WS_WOUTT) + (size_t)l * D * D + k0, mrows, D, kl, D}; pg8::StaticOrder S; S.init(mrows, D, gg, cc);
.LBB0_1181:
.LBB0_1182:
	s_mov_b32 s8, 0
	s_movk_i32 s3, 0x480
	s_movk_i32 s11, 0x50
	v_readlane_b32 s30, v253, 35
	v_readlane_b32 s17, v253, 34

; __global__ void __launch_bounds__(NWAVES * 64, 2) hybrid_fwd(Args A) {
;     ...
;                 if (s == 3) { phase_post(A, C, l, split ? 8 : 0); go = split && C.bid < 8 && !rep; k0 = 0; kl = KSPLIT; gg = 8; cc = C.bid; mrows = MS; roff = (size_t)MP * D; }
;                 if (go) { pg8::Gemm g{WS_PTR(const bf16, WS_XN) + roff + k0, WS_PTR(const bf16, WS_WOUTT) + (size_t)l * D * D + k0, mrows, D, kl, D}; pg8::StaticOrder S; S.init(mrows, D, gg, cc);
.LBB0_1188:
	v_readlane_b32 s52, v253, 36
	s_mov_b32 s8, 0
	s_movk_i32 s3, 0x480
	s_mov_b32 s17, 8
	s_mov_b32 s11, 1
	s_mov_b64 s[40:41], 0x4000000
	v_readlane_b32 s30, v253, 0
	v_readlane_b32 s53, v253, 37
